# gate/up SwiGLU epilogue: the 8 per-row rowss loads hoisted to the epilogue head (one wait instead of 8 load+store drains)
# speedup vs baseline: 1.0112x; 1.0072x over previous
; __device__ __forceinline__ unsigned pk_bf16(float lo, float hi) { f32x2 v = {lo, hi}; bf16x2_t b = __builtin_convertvector(v, bf16x2_t); return __builtin_bit_cast(unsigned, b); }
;     __device__ __forceinline__ void operator()(const f32x4 (&acc)[2][2][4][2], const Unit& u, int wr, int wc, int fr, int fq) const {
;         const int row0 = u.pm * BM + wr * 64 + fr; const int col0 = u.pn * HALF + wc * 32 + 8 * fq;
;         const float* bp = bias + (size_t)((u.pm * BM) >> 14) * 5632 + u.pn * BM + wc * 32 + 8 * fq;
;         f32x4 bz[2][2];
; #pragma unroll
;         for (int bj = 0; bj < 2; ++bj)
; #pragma unroll
;             for (int n = 0; n < 2; ++n) bz[bj][n] = *(const f32x4*)(bp + bj * HALF + 4 * n);
; #pragma unroll
;         for (int ai = 0; ai < 2; ++ai)
; #pragma unroll
;             for (int m = 0; m < 4; ++m) {
;                 float o[8]; const float rv = rsqrtf(rowss[row0 + ai * HALF + m * 16] * (1.0f / 1024.0f) + 1e-6f);
; #pragma unroll
;                 for (int n = 0; n < 2; ++n)
; #pragma unroll
;                     for (int j = 0; j < 4; ++j) { const float g = acc[ai][0][m][n][j] * rv + bz[0][n][j], up = acc[ai][1][m][n][j] * rv + bz[1][n][j];
;                         o[4 * n + j] = g * __builtin_amdgcn_rcpf(1.0f + __expf(-g)) * up; }
;                 u32x4 w; w.x = pk_bf16(o[0], o[1]); w.y = pk_bf16(o[2], o[3]); w.z = pk_bf16(o[4], o[5]); w.w = pk_bf16(o[6], o[7]);
;                 *(u32x4*)(act + (size_t)(row0 + ai * HALF + m * 16) * 2816 + col0) = w;
;             }
.LBB0_907:
	s_ashr_i32 s4, s34, 6
	s_mul_hi_i32 s5, s4, 0x5800
	s_mulk_i32 s4, 0x5800
	v_lshl_add_u32 v156, s34, 8, v162
	s_add_u32 s34, s14, s4
	s_addc_u32 s37, s15, s5
	s_lshl_b32 s4, s31, 8
	s_ashr_i32 s5, s4, 31
	s_lshl_b64 s[4:5], s[4:5], 2
	s_add_u32 s4, s34, s4
	s_addc_u32 s5, s37, s5
	s_add_u32 s4, s4, s30
	v_ashrrev_i32_e32 v157, 31, v156
	s_addc_u32 s5, s5, 0
	v_lshl_add_u64 v[158:159], v[156:157], 2, s[42:43]
	global_load_dwordx4 v[36:39], v166, s[4:5] offset:16
	global_load_dwordx4 v[44:47], v166, s[4:5]
	global_load_dwordx4 v[32:35], v166, s[4:5] offset:528
	global_load_dwordx4 v[40:43], v166, s[4:5] offset:512
	global_load_dword v157, v[158:159], off
	global_load_dword v186, v[158:159], off offset:64
	global_load_dword v187, v[158:159], off offset:128
	global_load_dword v188, v[158:159], off offset:192
	global_load_dword v189, v[158:159], off offset:512
	global_load_dword v190, v[158:159], off offset:576
	global_load_dword v191, v[158:159], off offset:640
	global_load_dword v192, v[158:159], off offset:704
	v_lshl_or_b32 v160, s31, 7, v164
	v_ashrrev_i32_e32 v161, 31, v160
	s_movk_i32 s12, 0x1600
	s_mov_b64 s[54:55], -1
	s_waitcnt vmcnt(0)
	v_fmamk_f32 v157, v157, 0x3a800000, v227
	v_cmp_gt_f32_e32 vcc, s36, v157
	v_mul_f32_e32 v167, 0x4b800000, v157
	s_nop 0
	v_cndmask_b32_e32 v157, v157, v167, vcc
	v_rsq_f32_e32 v157, v157
	s_nop 0
	v_mul_f32_e32 v167, 0x45800000, v157
	v_cndmask_b32_e32 v168, v157, v167, vcc
	v_pk_fma_f32 v[142:143], v[142:143], v[168:169], v[44:45] op_sel_hi:[1,0,1]
	v_pk_fma_f32 v[134:135], v[134:135], v[168:169], v[40:41] op_sel_hi:[1,0,1]
	v_mul_f32_e32 v157, 0xbfb8aa3b, v142
	v_exp_f32_e32 v157, v157
	v_pk_fma_f32 v[136:137], v[136:137], v[168:169], v[42:43] op_sel_hi:[1,0,1]
	v_pk_fma_f32 v[138:139], v[138:139], v[168:169], v[36:37] op_sel_hi:[1,0,1]
	v_pk_fma_f32 v[130:131], v[130:131], v[168:169], v[32:33] op_sel_hi:[1,0,1]
	v_add_f32_e32 v157, 1.0, v157
	v_rcp_f32_e32 v170, v157
	v_mul_f32_e32 v157, 0xbfb8aa3b, v143
	v_exp_f32_e32 v157, v157
	v_pk_fma_f32 v[132:133], v[132:133], v[168:169], v[34:35] op_sel_hi:[1,0,1]
	v_add_f32_e32 v157, 1.0, v157
	v_rcp_f32_e32 v171, v157
	s_nop 0
	v_pk_mul_f32 v[142:143], v[142:143], v[170:171]
	s_nop 0
	v_pk_mul_f32 v[134:135], v[134:135], v[142:143]
	v_pk_fma_f32 v[142:143], v[144:145], v[168:169], v[46:47] op_sel_hi:[1,0,1]
	s_nop 0
	v_mul_f32_e32 v144, 0xbfb8aa3b, v142
	v_mul_f32_e32 v145, 0xbfb8aa3b, v143
	v_exp_f32_e32 v144, v144
	v_exp_f32_e32 v145, v145
	v_add_f32_e32 v144, 1.0, v144
	v_add_f32_e32 v145, 1.0, v145
	v_rcp_f32_e32 v144, v144
	v_rcp_f32_e32 v145, v145
	s_nop 0
	v_pk_mul_f32 v[142:143], v[142:143], v[144:145]
	s_nop 0
	v_pk_mul_f32 v[136:137], v[136:137], v[142:143]
	v_mul_f32_e32 v142, 0xbfb8aa3b, v138
	v_mul_f32_e32 v143, 0xbfb8aa3b, v139
	v_exp_f32_e32 v142, v142
	v_exp_f32_e32 v143, v143
	v_add_f32_e32 v142, 1.0, v142
	v_add_f32_e32 v143, 1.0, v143
	v_rcp_f32_e32 v142, v142
	v_rcp_f32_e32 v143, v143
	s_nop 0
	v_pk_mul_f32 v[138:139], v[138:139], v[142:143]
	s_nop 0
	v_pk_mul_f32 v[138:139], v[130:131], v[138:139]
	v_pk_fma_f32 v[130:131], v[140:141], v[168:169], v[38:39] op_sel_hi:[1,0,1]
	s_nop 0
	v_mul_f32_e32 v140, 0xbfb8aa3b, v130
	v_mul_f32_e32 v141, 0xbfb8aa3b, v131
	v_exp_f32_e32 v140, v140
	v_exp_f32_e32 v141, v141
	v_add_f32_e32 v140, 1.0, v140
	v_add_f32_e32 v141, 1.0, v141
	v_rcp_f32_e32 v140, v140
	v_rcp_f32_e32 v141, v141
	s_nop 0
	v_pk_mul_f32 v[130:131], v[130:131], v[140:141]
	s_nop 0
	v_pk_mul_f32 v[140:141], v[132:133], v[130:131]
	v_cvt_pk_bf16_f32 v130, v134, v135
	v_mov_b64_e32 v[134:135], s[2:3]
	v_cvt_pk_bf16_f32 v131, v136, v137
	v_cvt_pk_bf16_f32 v132, v138, v139
	v_mad_i64_i32 v[138:139], s[4:5], v156, s12, v[134:135]
	v_lshlrev_b64 v[136:137], 1, v[160:161]
	v_cvt_pk_bf16_f32 v133, v140, v141
	v_lshl_add_u64 v[138:139], v[138:139], 0, v[136:137]
	global_store_dwordx4 v[138:139], v[130:133], off
	s_nop 1
	v_or_b32_e32 v130, 16, v156
	v_fmamk_f32 v131, v186, 0x3a800000, v227
	v_cmp_gt_f32_e32 vcc, s36, v131
	v_mul_f32_e32 v132, 0x4b800000, v131
	s_nop 0
	v_cndmask_b32_e32 v131, v131, v132, vcc
	v_rsq_f32_e32 v131, v131
	s_nop 0
	v_mul_f32_e32 v132, 0x45800000, v131
	v_cndmask_b32_e32 v132, v131, v132, vcc
	v_pk_fma_f32 v[124:125], v[124:125], v[132:133], v[44:45] op_sel_hi:[1,0,1]
	v_pk_fma_f32 v[116:117], v[116:117], v[132:133], v[40:41] op_sel_hi:[1,0,1]
	v_mul_f32_e32 v131, 0xbfb8aa3b, v124
	v_exp_f32_e32 v131, v131
	v_pk_fma_f32 v[118:119], v[118:119], v[132:133], v[42:43] op_sel_hi:[1,0,1]
	v_pk_fma_f32 v[120:121], v[120:121], v[132:133], v[36:37] op_sel_hi:[1,0,1]
	v_pk_fma_f32 v[112:113], v[112:113], v[132:133], v[32:33] op_sel_hi:[1,0,1]
	v_add_f32_e32 v131, 1.0, v131
	v_rcp_f32_e32 v138, v131
	v_mul_f32_e32 v131, 0xbfb8aa3b, v125
	v_exp_f32_e32 v131, v131
	v_pk_fma_f32 v[114:115], v[114:115], v[132:133], v[34:35] op_sel_hi:[1,0,1]
	v_add_f32_e32 v131, 1.0, v131
	v_rcp_f32_e32 v139, v131
	s_nop 0
	v_pk_mul_f32 v[124:125], v[124:125], v[138:139]
	s_nop 0
	v_pk_mul_f32 v[116:117], v[116:117], v[124:125]
	v_pk_fma_f32 v[124:125], v[126:127], v[132:133], v[46:47] op_sel_hi:[1,0,1]
	s_nop 0
	v_mul_f32_e32 v126, 0xbfb8aa3b, v124
	v_mul_f32_e32 v127, 0xbfb8aa3b, v125
	v_exp_f32_e32 v126, v126
	v_exp_f32_e32 v127, v127
	v_add_f32_e32 v126, 1.0, v126
	v_add_f32_e32 v127, 1.0, v127
	v_rcp_f32_e32 v126, v126
	v_rcp_f32_e32 v127, v127
	s_nop 0
	v_pk_mul_f32 v[124:125], v[124:125], v[126:127]
	s_nop 0
	v_pk_mul_f32 v[118:119], v[118:119], v[124:125]
	v_mul_f32_e32 v124, 0xbfb8aa3b, v120
	v_mul_f32_e32 v125, 0xbfb8aa3b, v121
	v_exp_f32_e32 v124, v124
	v_exp_f32_e32 v125, v125
	v_add_f32_e32 v124, 1.0, v124
; __device__ __forceinline__ unsigned pk_bf16(float lo, float hi) { f32x2 v = {lo, hi}; bf16x2_t b = __builtin_convertvector(v, bf16x2_t); return __builtin_bit_cast(unsigned, b); }
;     __device__ __forceinline__ void operator()(const f32x4 (&acc)[2][2][4][2], const Unit& u, int wr, int wc, int fr, int fq) const {
;     ...
;             for (int m = 0; m < 4; ++m) {
;                 float o[8]; const float rv = rsqrtf(rowss[row0 + ai * HALF + m * 16] * (1.0f / 1024.0f) + 1e-6f);
; #pragma unroll
;                 for (int n = 0; n < 2; ++n)
; #pragma unroll
;                     for (int j = 0; j < 4; ++j) { const float g = acc[ai][0][m][n][j] * rv + bz[0][n][j], up = acc[ai][1][m][n][j] * rv + bz[1][n][j];
;                         o[4 * n + j] = g * __builtin_amdgcn_rcpf(1.0f + __expf(-g)) * up; }
;                 u32x4 w; w.x = pk_bf16(o[0], o[1]); w.y = pk_bf16(o[2], o[3]); w.z = pk_bf16(o[4], o[5]); w.w = pk_bf16(o[6], o[7]);
;                 *(u32x4*)(act + (size_t)(row0 + ai * HALF + m * 16) * 2816 + col0) = w;
	v_add_f32_e32 v125, 1.0, v125
	v_rcp_f32_e32 v124, v124
	v_rcp_f32_e32 v125, v125
	s_nop 0
	v_pk_mul_f32 v[120:121], v[120:121], v[124:125]
	s_nop 0
	v_pk_mul_f32 v[120:121], v[112:113], v[120:121]
	v_pk_fma_f32 v[112:113], v[122:123], v[132:133], v[38:39] op_sel_hi:[1,0,1]
	s_nop 0
	v_mul_f32_e32 v122, 0xbfb8aa3b, v112
	v_mul_f32_e32 v123, 0xbfb8aa3b, v113
	v_exp_f32_e32 v122, v122
	v_exp_f32_e32 v123, v123
	v_add_f32_e32 v122, 1.0, v122
	v_add_f32_e32 v123, 1.0, v123
	v_rcp_f32_e32 v122, v122
	v_rcp_f32_e32 v123, v123
	s_nop 0
	v_pk_mul_f32 v[112:113], v[112:113], v[122:123]
	s_nop 0
	v_pk_mul_f32 v[122:123], v[114:115], v[112:113]
	v_cvt_pk_bf16_f32 v112, v116, v117
	v_mad_i64_i32 v[116:117], s[4:5], v130, s12, v[134:135]
	v_cvt_pk_bf16_f32 v113, v118, v119
	v_cvt_pk_bf16_f32 v114, v120, v121
	v_cvt_pk_bf16_f32 v115, v122, v123
	v_lshl_add_u64 v[116:117], v[116:117], 0, v[136:137]
	global_store_dwordx4 v[116:117], v[112:115], off
	s_nop 1
	v_or_b32_e32 v112, 32, v156
	v_fmamk_f32 v113, v187, 0x3a800000, v227
	v_cmp_gt_f32_e32 vcc, s36, v113
	v_mul_f32_e32 v114, 0x4b800000, v113
	s_nop 0
	v_cndmask_b32_e32 v113, v113, v114, vcc
	v_rsq_f32_e32 v113, v113
	s_nop 0
	v_mul_f32_e32 v114, 0x45800000, v113
	v_cndmask_b32_e32 v114, v113, v114, vcc
	v_pk_fma_f32 v[108:109], v[108:109], v[114:115], v[44:45] op_sel_hi:[1,0,1]
	v_pk_fma_f32 v[100:101], v[100:101], v[114:115], v[40:41] op_sel_hi:[1,0,1]
	v_mul_f32_e32 v113, 0xbfb8aa3b, v108
	v_exp_f32_e32 v113, v113
	v_pk_fma_f32 v[102:103], v[102:103], v[114:115], v[42:43] op_sel_hi:[1,0,1]
	v_pk_fma_f32 v[104:105], v[104:105], v[114:115], v[36:37] op_sel_hi:[1,0,1]
	v_pk_fma_f32 v[96:97], v[96:97], v[114:115], v[32:33] op_sel_hi:[1,0,1]
	v_add_f32_e32 v113, 1.0, v113
	v_rcp_f32_e32 v116, v113
	v_mul_f32_e32 v113, 0xbfb8aa3b, v109
	v_exp_f32_e32 v113, v113
	v_pk_fma_f32 v[98:99], v[98:99], v[114:115], v[34:35] op_sel_hi:[1,0,1]
	v_add_f32_e32 v113, 1.0, v113
	v_rcp_f32_e32 v117, v113
	s_nop 0
	v_pk_mul_f32 v[108:109], v[108:109], v[116:117]
	s_nop 0
	v_pk_mul_f32 v[100:101], v[100:101], v[108:109]
	v_pk_fma_f32 v[108:109], v[110:111], v[114:115], v[46:47] op_sel_hi:[1,0,1]
	s_nop 0
	v_mul_f32_e32 v110, 0xbfb8aa3b, v108
	v_mul_f32_e32 v111, 0xbfb8aa3b, v109
	v_exp_f32_e32 v110, v110
	v_exp_f32_e32 v111, v111
	v_add_f32_e32 v110, 1.0, v110
	v_add_f32_e32 v111, 1.0, v111
	v_rcp_f32_e32 v110, v110
	v_rcp_f32_e32 v111, v111
	s_nop 0
	v_pk_mul_f32 v[108:109], v[108:109], v[110:111]
	s_nop 0
	v_pk_mul_f32 v[102:103], v[102:103], v[108:109]
	v_mul_f32_e32 v108, 0xbfb8aa3b, v104
	v_mul_f32_e32 v109, 0xbfb8aa3b, v105
	v_exp_f32_e32 v108, v108
	v_exp_f32_e32 v109, v109
	v_add_f32_e32 v108, 1.0, v108
	v_add_f32_e32 v109, 1.0, v109
	v_rcp_f32_e32 v108, v108
	v_rcp_f32_e32 v109, v109
	s_nop 0
	v_pk_mul_f32 v[104:105], v[104:105], v[108:109]
	s_nop 0
	v_pk_mul_f32 v[104:105], v[96:97], v[104:105]
	v_pk_fma_f32 v[96:97], v[106:107], v[114:115], v[38:39] op_sel_hi:[1,0,1]
	s_nop 0
	v_mul_f32_e32 v106, 0xbfb8aa3b, v96
	v_mul_f32_e32 v107, 0xbfb8aa3b, v97
	v_exp_f32_e32 v106, v106
	v_exp_f32_e32 v107, v107
	v_add_f32_e32 v106, 1.0, v106
	v_add_f32_e32 v107, 1.0, v107
	v_rcp_f32_e32 v106, v106
	v_rcp_f32_e32 v107, v107
	s_nop 0
	v_pk_mul_f32 v[96:97], v[96:97], v[106:107]
	s_nop 0
	v_pk_mul_f32 v[106:107], v[98:99], v[96:97]
	v_cvt_pk_bf16_f32 v96, v100, v101
	v_mad_i64_i32 v[100:101], s[4:5], v112, s12, v[134:135]
	v_cvt_pk_bf16_f32 v97, v102, v103
	v_cvt_pk_bf16_f32 v98, v104, v105
	v_cvt_pk_bf16_f32 v99, v106, v107
	v_lshl_add_u64 v[100:101], v[100:101], 0, v[136:137]
	global_store_dwordx4 v[100:101], v[96:99], off
	s_nop 1
	v_or_b32_e32 v96, 48, v156
	v_fmamk_f32 v97, v188, 0x3a800000, v227
	v_cmp_gt_f32_e32 vcc, s36, v97
	v_mul_f32_e32 v98, 0x4b800000, v97
	s_nop 0
	v_cndmask_b32_e32 v97, v97, v98, vcc
	v_rsq_f32_e32 v97, v97
	s_nop 0
	v_mul_f32_e32 v98, 0x45800000, v97
	v_cndmask_b32_e32 v98, v97, v98, vcc
	v_pk_fma_f32 v[92:93], v[92:93], v[98:99], v[44:45] op_sel_hi:[1,0,1]
	v_pk_fma_f32 v[84:85], v[84:85], v[98:99], v[40:41] op_sel_hi:[1,0,1]
	v_mul_f32_e32 v97, 0xbfb8aa3b, v92
	v_exp_f32_e32 v97, v97
	v_pk_fma_f32 v[86:87], v[86:87], v[98:99], v[42:43] op_sel_hi:[1,0,1]
	v_pk_fma_f32 v[88:89], v[88:89], v[98:99], v[36:37] op_sel_hi:[1,0,1]
	v_pk_fma_f32 v[80:81], v[80:81], v[98:99], v[32:33] op_sel_hi:[1,0,1]
	v_add_f32_e32 v97, 1.0, v97
	v_rcp_f32_e32 v100, v97
	v_mul_f32_e32 v97, 0xbfb8aa3b, v93
	v_exp_f32_e32 v97, v97
	v_pk_fma_f32 v[82:83], v[82:83], v[98:99], v[34:35] op_sel_hi:[1,0,1]
	v_add_f32_e32 v97, 1.0, v97
	v_rcp_f32_e32 v101, v97
	s_nop 0
	v_pk_mul_f32 v[92:93], v[92:93], v[100:101]
	s_nop 0
	v_pk_mul_f32 v[84:85], v[84:85], v[92:93]
	v_pk_fma_f32 v[92:93], v[94:95], v[98:99], v[46:47] op_sel_hi:[1,0,1]
	s_nop 0
	v_mul_f32_e32 v94, 0xbfb8aa3b, v92
	v_mul_f32_e32 v95, 0xbfb8aa3b, v93
	v_exp_f32_e32 v94, v94
	v_exp_f32_e32 v95, v95
	v_add_f32_e32 v94, 1.0, v94
	v_add_f32_e32 v95, 1.0, v95
	v_rcp_f32_e32 v94, v94
	v_rcp_f32_e32 v95, v95
	s_nop 0
	v_pk_mul_f32 v[92:93], v[92:93], v[94:95]
	s_nop 0
	v_pk_mul_f32 v[86:87], v[86:87], v[92:93]
	v_mul_f32_e32 v92, 0xbfb8aa3b, v88
	v_mul_f32_e32 v93, 0xbfb8aa3b, v89
	v_exp_f32_e32 v92, v92
	v_exp_f32_e32 v93, v93
	v_add_f32_e32 v92, 1.0, v92
	v_add_f32_e32 v93, 1.0, v93
	v_rcp_f32_e32 v92, v92
	v_rcp_f32_e32 v93, v93
	s_nop 0
	v_pk_mul_f32 v[88:89], v[88:89], v[92:93]
	s_nop 0
	v_pk_mul_f32 v[88:89], v[80:81], v[88:89]
	v_pk_fma_f32 v[80:81], v[90:91], v[98:99], v[38:39] op_sel_hi:[1,0,1]
	s_nop 0
	v_mul_f32_e32 v90, 0xbfb8aa3b, v80
	v_mul_f32_e32 v91, 0xbfb8aa3b, v81
	v_exp_f32_e32 v90, v90
	v_exp_f32_e32 v91, v91
	v_add_f32_e32 v90, 1.0, v90
; __device__ __forceinline__ unsigned pk_bf16(float lo, float hi) { f32x2 v = {lo, hi}; bf16x2_t b = __builtin_convertvector(v, bf16x2_t); return __builtin_bit_cast(unsigned, b); }
;     __device__ __forceinline__ void operator()(const f32x4 (&acc)[2][2][4][2], const Unit& u, int wr, int wc, int fr, int fq) const {
;     ...
;             for (int m = 0; m < 4; ++m) {
;                 float o[8]; const float rv = rsqrtf(rowss[row0 + ai * HALF + m * 16] * (1.0f / 1024.0f) + 1e-6f);
; #pragma unroll
;                 for (int n = 0; n < 2; ++n)
; #pragma unroll
;                     for (int j = 0; j < 4; ++j) { const float g = acc[ai][0][m][n][j] * rv + bz[0][n][j], up = acc[ai][1][m][n][j] * rv + bz[1][n][j];
;                         o[4 * n + j] = g * __builtin_amdgcn_rcpf(1.0f + __expf(-g)) * up; }
;                 u32x4 w; w.x = pk_bf16(o[0], o[1]); w.y = pk_bf16(o[2], o[3]); w.z = pk_bf16(o[4], o[5]); w.w = pk_bf16(o[6], o[7]);
;                 *(u32x4*)(act + (size_t)(row0 + ai * HALF + m * 16) * 2816 + col0) = w;
	v_add_f32_e32 v91, 1.0, v91
	v_rcp_f32_e32 v90, v90
	v_rcp_f32_e32 v91, v91
	s_nop 0
	v_pk_mul_f32 v[80:81], v[80:81], v[90:91]
	s_nop 0
	v_pk_mul_f32 v[90:91], v[82:83], v[80:81]
	v_cvt_pk_bf16_f32 v80, v84, v85
	v_mad_i64_i32 v[84:85], s[4:5], v96, s12, v[134:135]
	v_cvt_pk_bf16_f32 v81, v86, v87
	v_cvt_pk_bf16_f32 v82, v88, v89
	v_cvt_pk_bf16_f32 v83, v90, v91
	v_lshl_add_u64 v[84:85], v[84:85], 0, v[136:137]
	global_store_dwordx4 v[84:85], v[80:83], off
	s_nop 0
	s_nop 0
	v_add_u32_e32 v81, 0x80, v156
	v_fmamk_f32 v80, v189, 0x3a800000, v227
	v_cmp_gt_f32_e32 vcc, s36, v80
	v_mul_f32_e32 v82, 0x4b800000, v80
	s_nop 0
	v_cndmask_b32_e32 v80, v80, v82, vcc
	v_rsq_f32_e32 v80, v80
	s_nop 0
	v_mul_f32_e32 v82, 0x45800000, v80
	v_cndmask_b32_e32 v80, v80, v82, vcc
	v_pk_fma_f32 v[76:77], v[76:77], v[80:81], v[44:45] op_sel_hi:[1,0,1]
	v_pk_fma_f32 v[68:69], v[68:69], v[80:81], v[40:41] op_sel_hi:[1,0,1]
	v_mul_f32_e32 v82, 0xbfb8aa3b, v76
	v_mul_f32_e32 v83, 0xbfb8aa3b, v77
	v_exp_f32_e32 v82, v82
	v_exp_f32_e32 v83, v83
	v_pk_fma_f32 v[70:71], v[70:71], v[80:81], v[42:43] op_sel_hi:[1,0,1]
	v_pk_fma_f32 v[72:73], v[72:73], v[80:81], v[36:37] op_sel_hi:[1,0,1]
	v_add_f32_e32 v82, 1.0, v82
	v_add_f32_e32 v83, 1.0, v83
	v_rcp_f32_e32 v82, v82
	v_rcp_f32_e32 v83, v83
	v_pk_fma_f32 v[64:65], v[64:65], v[80:81], v[32:33] op_sel_hi:[1,0,1]
	v_pk_fma_f32 v[66:67], v[66:67], v[80:81], v[34:35] op_sel_hi:[1,0,1]
	v_pk_mul_f32 v[76:77], v[76:77], v[82:83]
	s_nop 0
	v_pk_mul_f32 v[68:69], v[68:69], v[76:77]
	v_pk_fma_f32 v[76:77], v[78:79], v[80:81], v[46:47] op_sel_hi:[1,0,1]
	s_nop 0
	v_mul_f32_e32 v78, 0xbfb8aa3b, v76
	v_mul_f32_e32 v79, 0xbfb8aa3b, v77
	v_exp_f32_e32 v78, v78
	v_exp_f32_e32 v79, v79
	v_add_f32_e32 v78, 1.0, v78
	v_add_f32_e32 v79, 1.0, v79
	v_rcp_f32_e32 v78, v78
	v_rcp_f32_e32 v79, v79
	s_nop 0
	v_pk_mul_f32 v[76:77], v[76:77], v[78:79]
	s_nop 0
	v_pk_mul_f32 v[70:71], v[70:71], v[76:77]
	v_mul_f32_e32 v76, 0xbfb8aa3b, v72
	v_mul_f32_e32 v77, 0xbfb8aa3b, v73
	v_exp_f32_e32 v76, v76
	v_exp_f32_e32 v77, v77
	v_add_f32_e32 v76, 1.0, v76
	v_add_f32_e32 v77, 1.0, v77
	v_rcp_f32_e32 v76, v76
	v_rcp_f32_e32 v77, v77
	s_nop 0
	v_pk_mul_f32 v[72:73], v[72:73], v[76:77]
	s_nop 0
	v_pk_mul_f32 v[72:73], v[64:65], v[72:73]
	v_pk_fma_f32 v[64:65], v[74:75], v[80:81], v[38:39] op_sel_hi:[1,0,1]
	s_nop 0
	v_mul_f32_e32 v74, 0xbfb8aa3b, v64
	v_mul_f32_e32 v75, 0xbfb8aa3b, v65
	v_exp_f32_e32 v74, v74
	v_exp_f32_e32 v75, v75
	v_add_f32_e32 v74, 1.0, v74
	v_add_f32_e32 v75, 1.0, v75
	v_rcp_f32_e32 v74, v74
	v_rcp_f32_e32 v75, v75
	s_nop 0
	v_pk_mul_f32 v[64:65], v[64:65], v[74:75]
	s_nop 0
	v_pk_mul_f32 v[74:75], v[66:67], v[64:65]
	v_cvt_pk_bf16_f32 v64, v68, v69
	v_mad_i64_i32 v[68:69], s[4:5], v81, s12, v[134:135]
	v_cvt_pk_bf16_f32 v65, v70, v71
	v_cvt_pk_bf16_f32 v66, v72, v73
	v_cvt_pk_bf16_f32 v67, v74, v75
	v_lshl_add_u64 v[68:69], v[68:69], 0, v[136:137]
	global_store_dwordx4 v[68:69], v[64:67], off
	s_nop 0
	s_nop 0
	v_add_u32_e32 v65, 0x90, v156
	v_fmamk_f32 v64, v190, 0x3a800000, v227
	v_cmp_gt_f32_e32 vcc, s36, v64
	v_mul_f32_e32 v66, 0x4b800000, v64
	s_nop 0
	v_cndmask_b32_e32 v64, v64, v66, vcc
	v_rsq_f32_e32 v64, v64
	s_nop 0
	v_mul_f32_e32 v66, 0x45800000, v64
	v_cndmask_b32_e32 v64, v64, v66, vcc
	v_pk_fma_f32 v[60:61], v[60:61], v[64:65], v[44:45] op_sel_hi:[1,0,1]
	v_pk_fma_f32 v[52:53], v[52:53], v[64:65], v[40:41] op_sel_hi:[1,0,1]
	v_mul_f32_e32 v66, 0xbfb8aa3b, v60
	v_mul_f32_e32 v67, 0xbfb8aa3b, v61
	v_exp_f32_e32 v66, v66
	v_exp_f32_e32 v67, v67
	v_pk_fma_f32 v[54:55], v[54:55], v[64:65], v[42:43] op_sel_hi:[1,0,1]
	v_pk_fma_f32 v[56:57], v[56:57], v[64:65], v[36:37] op_sel_hi:[1,0,1]
	v_add_f32_e32 v66, 1.0, v66
	v_add_f32_e32 v67, 1.0, v67
	v_rcp_f32_e32 v66, v66
	v_rcp_f32_e32 v67, v67
	v_pk_fma_f32 v[48:49], v[48:49], v[64:65], v[32:33] op_sel_hi:[1,0,1]
	v_pk_fma_f32 v[50:51], v[50:51], v[64:65], v[34:35] op_sel_hi:[1,0,1]
	v_pk_mul_f32 v[60:61], v[60:61], v[66:67]
	s_nop 0
	v_pk_mul_f32 v[52:53], v[52:53], v[60:61]
	v_pk_fma_f32 v[60:61], v[62:63], v[64:65], v[46:47] op_sel_hi:[1,0,1]
	s_nop 0
	v_mul_f32_e32 v62, 0xbfb8aa3b, v60
	v_mul_f32_e32 v63, 0xbfb8aa3b, v61
	v_exp_f32_e32 v62, v62
	v_exp_f32_e32 v63, v63
	v_add_f32_e32 v62, 1.0, v62
	v_add_f32_e32 v63, 1.0, v63
	v_rcp_f32_e32 v62, v62
	v_rcp_f32_e32 v63, v63
	s_nop 0
	v_pk_mul_f32 v[60:61], v[60:61], v[62:63]
	s_nop 0
	v_pk_mul_f32 v[54:55], v[54:55], v[60:61]
	v_mul_f32_e32 v60, 0xbfb8aa3b, v56
	v_mul_f32_e32 v61, 0xbfb8aa3b, v57
	v_exp_f32_e32 v60, v60
	v_exp_f32_e32 v61, v61
	v_add_f32_e32 v60, 1.0, v60
	v_add_f32_e32 v61, 1.0, v61
	v_rcp_f32_e32 v60, v60
	v_rcp_f32_e32 v61, v61
	s_nop 0
	v_pk_mul_f32 v[56:57], v[56:57], v[60:61]
	s_nop 0
	v_pk_mul_f32 v[56:57], v[48:49], v[56:57]
	v_pk_fma_f32 v[48:49], v[58:59], v[64:65], v[38:39] op_sel_hi:[1,0,1]
	s_nop 0
	v_mul_f32_e32 v58, 0xbfb8aa3b, v48
	v_mul_f32_e32 v59, 0xbfb8aa3b, v49
	v_exp_f32_e32 v58, v58
	v_exp_f32_e32 v59, v59
	v_add_f32_e32 v58, 1.0, v58
	v_add_f32_e32 v59, 1.0, v59
	v_rcp_f32_e32 v58, v58
	v_rcp_f32_e32 v59, v59
	s_nop 0
	v_pk_mul_f32 v[48:49], v[48:49], v[58:59]
	s_nop 0
	v_pk_mul_f32 v[58:59], v[50:51], v[48:49]
	v_cvt_pk_bf16_f32 v48, v52, v53
	v_mad_i64_i32 v[52:53], s[4:5], v65, s12, v[134:135]
; __device__ __forceinline__ unsigned pk_bf16(float lo, float hi) { f32x2 v = {lo, hi}; bf16x2_t b = __builtin_convertvector(v, bf16x2_t); return __builtin_bit_cast(unsigned, b); }
; #define PG8_BAR __builtin_amdgcn_s_barrier()
;     __device__ __forceinline__ void operator()(const f32x4 (&acc)[2][2][4][2], const Unit& u, int wr, int wc, int fr, int fq) const {
;     ...
;             for (int m = 0; m < 4; ++m) {
;                 float o[8]; const float rv = rsqrtf(rowss[row0 + ai * HALF + m * 16] * (1.0f / 1024.0f) + 1e-6f);
; #pragma unroll
;                 for (int n = 0; n < 2; ++n)
; #pragma unroll
;                     for (int j = 0; j < 4; ++j) { const float g = acc[ai][0][m][n][j] * rv + bz[0][n][j], up = acc[ai][1][m][n][j] * rv + bz[1][n][j];
;                         o[4 * n + j] = g * __builtin_amdgcn_rcpf(1.0f + __expf(-g)) * up; }
;                 u32x4 w; w.x = pk_bf16(o[0], o[1]); w.y = pk_bf16(o[2], o[3]); w.z = pk_bf16(o[4], o[5]); w.w = pk_bf16(o[6], o[7]);
;                 *(u32x4*)(act + (size_t)(row0 + ai * HALF + m * 16) * 2816 + col0) = w;
; template <class Epi, class Sched, bool ALIGN_EPI = false, bool SP2 = false, bool F16 = false>
; __device__ __forceinline__ void gemm_phase(PG8_LAS unsigned char* lds, const Gemm g, const Sched& S, const Epi& E) {
;     ...
;         if constexpr (!Epi::AFTER_DRAIN) { E(acc, cur, wr, wc, fr, fq);
;     ...
;             if constexpr (Epi::PROBE2) { asm volatile("" ::: "memory"); E(acc, cur, wr, wc, fr, fq); }
;     ...
;             S.done(cur); }
;         if (!has_next) break;
; #pragma unroll
;         for (int a = 0; a < 2; ++a)
; #pragma unroll
;             for (int b = 0; b < 2; ++b)
; #pragma unroll
;                 for (int m = 0; m < 4; ++m)
; #pragma unroll
;                     for (int n = 0; n < 2; ++n) acc[a][b][m][n] = (f32x4){0.f, 0.f, 0.f, 0.f};
;         cur = nxt; cA = nA; cB = nB; ++ui;
;         if constexpr (ALIGN_EPI) { if (wr == 1) PG8_BAR; }
	v_cvt_pk_bf16_f32 v49, v54, v55
	v_cvt_pk_bf16_f32 v50, v56, v57
	v_cvt_pk_bf16_f32 v51, v58, v59
	v_lshl_add_u64 v[52:53], v[52:53], 0, v[136:137]
	global_store_dwordx4 v[52:53], v[48:51], off
	s_nop 0
	s_nop 0
	v_add_u32_e32 v49, 0xa0, v156
	v_fmamk_f32 v48, v191, 0x3a800000, v227
	v_cmp_gt_f32_e32 vcc, s36, v48
	v_mul_f32_e32 v50, 0x4b800000, v48
	s_nop 0
	v_cndmask_b32_e32 v48, v48, v50, vcc
	v_rsq_f32_e32 v48, v48
	s_nop 0
	v_mul_f32_e32 v50, 0x45800000, v48
	v_cndmask_b32_e32 v48, v48, v50, vcc
	v_pk_fma_f32 v[28:29], v[28:29], v[48:49], v[44:45] op_sel_hi:[1,0,1]
	v_pk_fma_f32 v[20:21], v[20:21], v[48:49], v[40:41] op_sel_hi:[1,0,1]
	v_mul_f32_e32 v50, 0xbfb8aa3b, v28
	v_mul_f32_e32 v51, 0xbfb8aa3b, v29
	v_exp_f32_e32 v50, v50
	v_exp_f32_e32 v51, v51
	v_pk_fma_f32 v[22:23], v[22:23], v[48:49], v[42:43] op_sel_hi:[1,0,1]
	v_pk_fma_f32 v[24:25], v[24:25], v[48:49], v[36:37] op_sel_hi:[1,0,1]
	v_add_f32_e32 v50, 1.0, v50
	v_add_f32_e32 v51, 1.0, v51
	v_rcp_f32_e32 v50, v50
	v_rcp_f32_e32 v51, v51
	v_pk_fma_f32 v[16:17], v[16:17], v[48:49], v[32:33] op_sel_hi:[1,0,1]
	v_pk_fma_f32 v[18:19], v[18:19], v[48:49], v[34:35] op_sel_hi:[1,0,1]
	v_pk_mul_f32 v[28:29], v[28:29], v[50:51]
	s_nop 0
	v_pk_mul_f32 v[20:21], v[20:21], v[28:29]
	v_pk_fma_f32 v[28:29], v[30:31], v[48:49], v[46:47] op_sel_hi:[1,0,1]
	s_nop 0
	v_mul_f32_e32 v30, 0xbfb8aa3b, v28
	v_mul_f32_e32 v31, 0xbfb8aa3b, v29
	v_exp_f32_e32 v30, v30
	v_exp_f32_e32 v31, v31
	v_add_f32_e32 v30, 1.0, v30
	v_add_f32_e32 v31, 1.0, v31
	v_rcp_f32_e32 v30, v30
	v_rcp_f32_e32 v31, v31
	s_nop 0
	v_pk_mul_f32 v[28:29], v[28:29], v[30:31]
	s_nop 0
	v_pk_mul_f32 v[22:23], v[22:23], v[28:29]
	v_mul_f32_e32 v28, 0xbfb8aa3b, v24
	v_mul_f32_e32 v29, 0xbfb8aa3b, v25
	v_exp_f32_e32 v28, v28
	v_exp_f32_e32 v29, v29
	v_add_f32_e32 v28, 1.0, v28
	v_add_f32_e32 v29, 1.0, v29
	v_rcp_f32_e32 v28, v28
	v_rcp_f32_e32 v29, v29
	s_nop 0
	v_pk_mul_f32 v[24:25], v[24:25], v[28:29]
	s_nop 0
	v_pk_mul_f32 v[24:25], v[16:17], v[24:25]
	v_pk_fma_f32 v[16:17], v[26:27], v[48:49], v[38:39] op_sel_hi:[1,0,1]
	s_nop 0
	v_mul_f32_e32 v26, 0xbfb8aa3b, v16
	v_mul_f32_e32 v27, 0xbfb8aa3b, v17
	v_exp_f32_e32 v26, v26
	v_exp_f32_e32 v27, v27
	v_add_f32_e32 v26, 1.0, v26
	v_add_f32_e32 v27, 1.0, v27
	v_rcp_f32_e32 v26, v26
	v_rcp_f32_e32 v27, v27
	s_nop 0
	v_pk_mul_f32 v[16:17], v[16:17], v[26:27]
	s_nop 0
	v_pk_mul_f32 v[26:27], v[18:19], v[16:17]
	v_cvt_pk_bf16_f32 v16, v20, v21
	v_mad_i64_i32 v[20:21], s[4:5], v49, s12, v[134:135]
	v_cvt_pk_bf16_f32 v17, v22, v23
	v_cvt_pk_bf16_f32 v18, v24, v25
	v_cvt_pk_bf16_f32 v19, v26, v27
	v_lshl_add_u64 v[20:21], v[20:21], 0, v[136:137]
	global_store_dwordx4 v[20:21], v[16:19], off
	s_nop 0
	s_nop 0
	v_add_u32_e32 v17, 0xb0, v156
	v_fmamk_f32 v16, v192, 0x3a800000, v227
	v_cmp_gt_f32_e32 vcc, s36, v16
	v_mul_f32_e32 v18, 0x4b800000, v16
	s_nop 0
	v_cndmask_b32_e32 v16, v16, v18, vcc
	v_rsq_f32_e32 v16, v16
	s_nop 0
	v_mul_f32_e32 v18, 0x45800000, v16
	v_cndmask_b32_e32 v16, v16, v18, vcc
	v_pk_fma_f32 v[12:13], v[12:13], v[16:17], v[44:45] op_sel_hi:[1,0,1]
	v_pk_fma_f32 v[4:5], v[4:5], v[16:17], v[40:41] op_sel_hi:[1,0,1]
	v_mul_f32_e32 v18, 0xbfb8aa3b, v12
	v_mul_f32_e32 v19, 0xbfb8aa3b, v13
	v_exp_f32_e32 v18, v18
	v_exp_f32_e32 v19, v19
	v_pk_fma_f32 v[6:7], v[6:7], v[16:17], v[42:43] op_sel_hi:[1,0,1]
	v_pk_fma_f32 v[8:9], v[8:9], v[16:17], v[36:37] op_sel_hi:[1,0,1]
	v_add_f32_e32 v18, 1.0, v18
	v_add_f32_e32 v19, 1.0, v19
	v_rcp_f32_e32 v18, v18
	v_rcp_f32_e32 v19, v19
	v_pk_fma_f32 v[0:1], v[0:1], v[16:17], v[32:33] op_sel_hi:[1,0,1]
	v_pk_fma_f32 v[2:3], v[2:3], v[16:17], v[34:35] op_sel_hi:[1,0,1]
	s_andn2_b64 vcc, exec, s[40:41]
	v_pk_mul_f32 v[12:13], v[12:13], v[18:19]
	s_nop 0
	v_pk_mul_f32 v[4:5], v[4:5], v[12:13]
	v_pk_fma_f32 v[12:13], v[14:15], v[16:17], v[46:47] op_sel_hi:[1,0,1]
	s_nop 0
	v_mul_f32_e32 v14, 0xbfb8aa3b, v12
	v_mul_f32_e32 v15, 0xbfb8aa3b, v13
	v_exp_f32_e32 v14, v14
	v_exp_f32_e32 v15, v15
	v_add_f32_e32 v14, 1.0, v14
	v_add_f32_e32 v15, 1.0, v15
	v_rcp_f32_e32 v14, v14
	v_rcp_f32_e32 v15, v15
	s_nop 0
	v_pk_mul_f32 v[12:13], v[12:13], v[14:15]
	s_nop 0
	v_pk_mul_f32 v[6:7], v[6:7], v[12:13]
	v_mul_f32_e32 v12, 0xbfb8aa3b, v8
	v_mul_f32_e32 v13, 0xbfb8aa3b, v9
	v_exp_f32_e32 v12, v12
	v_exp_f32_e32 v13, v13
	v_add_f32_e32 v12, 1.0, v12
	v_add_f32_e32 v13, 1.0, v13
	v_rcp_f32_e32 v12, v12
	v_rcp_f32_e32 v13, v13
	s_nop 0
	v_pk_mul_f32 v[8:9], v[8:9], v[12:13]
	s_nop 0
	v_pk_mul_f32 v[8:9], v[0:1], v[8:9]
	v_pk_fma_f32 v[0:1], v[10:11], v[16:17], v[38:39] op_sel_hi:[1,0,1]
	s_nop 0
	v_mul_f32_e32 v10, 0xbfb8aa3b, v0
	v_mul_f32_e32 v11, 0xbfb8aa3b, v1
	v_exp_f32_e32 v10, v10
	v_exp_f32_e32 v11, v11
	v_add_f32_e32 v10, 1.0, v10
	v_add_f32_e32 v11, 1.0, v11
	v_rcp_f32_e32 v10, v10
	v_rcp_f32_e32 v11, v11
	s_nop 0
	v_pk_mul_f32 v[0:1], v[0:1], v[10:11]
	s_nop 0
	v_pk_mul_f32 v[10:11], v[2:3], v[0:1]
	v_cvt_pk_bf16_f32 v0, v4, v5
	v_mad_i64_i32 v[4:5], s[4:5], v17, s12, v[134:135]
	v_cvt_pk_bf16_f32 v1, v6, v7
	v_cvt_pk_bf16_f32 v2, v8, v9
	v_cvt_pk_bf16_f32 v3, v10, v11
	v_lshl_add_u64 v[4:5], v[4:5], 0, v[136:137]
	global_store_dwordx4 v[4:5], v[0:3], off
	s_cbranch_vccnz .LBB0_900
	s_andn2_b64 vcc, exec, s[0:1]
	s_cbranch_vccnz .LBB0_899
	s_barrier
	s_branch .LBB0_899
